# GEMM stagger group static priority 3 instead of 1 (stacked on v17)
# baseline (speedup 1.0000x reference)
; DI int opaque_bid() { int b = blockIdx.x; asm volatile("" : "+s"(b)); return b; }
; #define PG8_STAGE(bufoff, gbase, voff) do { _Pragma("unroll") for (int _i = 0; _i < 2; ++_i) \
;         __builtin_amdgcn_global_load_lds((const unsigned*)((const char*)(gbase) + (voff)[_i]), (LAS unsigned*)(lds + (bufoff) + ldsw + _i * 8192), 16, 0, 0); } while (0)
; #define PG8_BAR __builtin_amdgcn_s_barrier()
; template <class Epi>
; DI void gemm_phase(int wv, LAS unsigned char* lds, const GemmD g, const Epi& E) {
;     ...
;     for (int i = 0; i < 2; ++i) { int R, C; stage_rc(tid * 16 + i * 8192, R, C); const int Rb = Epi::PERM ? ((R & ~31) + perm32(R & 31)) : R;
;         voffA[i] = (unsigned)(R * g.lda + C) * 2u; voffB[i] = (unsigned)(Rb * ldbe + C) * 2u; }
;     const size_t kstep = (size_t)(BK * 2);
;     const size_t hstepA = (size_t)HALF * g.lda * 2, hstepB = (size_t)HALF * ldbe * 2;
;     const unsigned ldsw = (unsigned)wid * 1024u;
;     const int aoff = lds_byte(wr * 64 + fr, fq * 8), boff = lds_byte(wc * 32 + fr, fq * 8);
;     ...
;     StaticOrder S; S.init(g.nM, g.nN, (int)gridDim.x, opaque_bid());
;     Unit cur, nxt; int ui = 0;
;     if (!S.next(0, cur)) return;
;     f32x4 acc[2][2][4][2];
; #pragma unroll
;     for (int a = 0; a < 2; ++a)
; #pragma unroll
;         for (int b = 0; b < 2; ++b)
; #pragma unroll
;             for (int m = 0; m < 4; ++m)
; #pragma unroll
;                 for (int n = 0; n < 2; ++n) acc[a][b][m][n] = (f32x4){0.f, 0.f, 0.f, 0.f};
;     bf16x8 At[4][2], B0[2][2], B1[2][2];
;     ...
;     const char* cA = (const char*)g.A + (size_t)cur.pm * 256 * g.lda * 2; const char* cB = (const char*)g.Bt + PG8_BROW(cur.pn) * (size_t)g.ldb * 2;
;     PG8_STAGE(PG8_SB(0, 0), cB, voffB); PG8_STAGE(PG8_SA(0, 0), cA, voffA); PG8_STAGE(PG8_SB(0, 1), cB + hstepB, voffB); PG8_STAGE(PG8_SA(0, 1), cA + hstepA, voffA);
;     if (wr == 1) PG8_BAR;
.LBB0_90:
	s_mov_b32 s1, s68
	v_mov_b32_e32 v3, v232
	s_mov_b32 s13, s55
	v_lshl_add_u32 v0, s1, 6, v3
	s_mul_i32 s56, s0, s30
	s_cmp_ge_i32 s13, s56
	v_readfirstlane_b32 s35, v0
	s_cbranch_scc1 .LBB0_84
	v_lshlrev_b32_e32 v6, 4, v0
	v_add_u32_e32 v4, 0x2000, v6
	v_ashrrev_i32_e32 v2, 31, v4
	v_lshrrev_b32_e32 v2, 22, v2
	v_add_u32_e32 v2, v4, v2
	v_ashrrev_i32_e32 v2, 10, v2
	s_waitcnt lgkmcnt(0)
	v_mul_i32_i24_e32 v5, 0x400, v2
	v_sub_u32_e32 v4, v4, v5
	v_lshrrev_b32_e32 v5, 4, v4
	v_bitop3_b32 v5, v5, v4, 32 bitop3:0x6c
	v_ashrrev_i32_e32 v4, 31, v5
	v_lshrrev_b32_e32 v4, 26, v4
	v_add_u32_e32 v7, v5, v4
	v_lshlrev_b32_e32 v8, 3, v2
	v_ashrrev_i32_e32 v4, 6, v7
	v_and_b32_e32 v8, -16, v8
	v_add_u32_e32 v8, v4, v8
	v_and_b32_e32 v9, 3, v4
	s_mov_b32 s2, 0x3fffe0
	v_lshrrev_b32_e32 v10, 2, v8
	v_lshlrev_b32_e32 v11, 1, v8
	v_and_b32_e32 v7, 0xc0, v7
	v_and_or_b32 v9, v8, s2, v9
	v_and_b32_e32 v10, 4, v10
	v_and_b32_e32 v11, 24, v11
	v_sub_u32_e32 v5, v5, v7
	v_or3_b32 v9, v9, v10, v11
	v_lshlrev_b32_e32 v10, 5, v2
	v_ashrrev_i16_sdwa v5, v244, sext(v5) dst_sel:DWORD dst_unused:UNUSED_PAD src0_sel:DWORD src1_sel:BYTE_0
	s_lshl_b32 s1, s31, 10
	v_and_b32_e32 v10, 32, v10
	v_bfe_i32 v5, v5, 0, 16
	v_mul_u32_u24_e32 v9, s1, v9
	v_add_u32_e32 v7, v10, v5
	v_lshlrev_b32_e32 v8, 11, v8
	v_add_lshl_u32 v130, v9, v7, 1
	v_lshl_add_u32 v132, v7, 1, v8
	v_bfe_i32 v7, v0, 27, 1
	v_lshrrev_b32_e32 v7, 22, v7
	v_add_u32_e32 v7, v6, v7
	v_and_b32_e32 v7, 0xfffffc00, v7
	v_sub_u32_e32 v6, v6, v7
	v_lshrrev_b32_e32 v7, 4, v6
	v_bitop3_b32 v8, v7, v6, 32 bitop3:0x6c
	v_ashrrev_i32_e32 v7, 31, v0
	v_lshrrev_b32_e32 v7, 26, v7
	v_ashrrev_i32_e32 v6, 31, v8
	v_add_u32_e32 v0, v0, v7
	v_lshrrev_b32_e32 v6, 26, v6
	v_ashrrev_i32_e32 v7, 6, v0
	v_add_u32_e32 v9, v8, v6
	v_lshlrev_b32_e32 v0, 3, v7
	v_ashrrev_i32_e32 v6, 6, v9
	v_and_b32_e32 v0, -16, v0
	v_add_u32_e32 v10, v6, v0
	v_and_b32_e32 v0, 3, v6
	v_lshrrev_b32_e32 v11, 2, v10
	v_lshlrev_b32_e32 v12, 1, v10
	v_and_or_b32 v0, v10, s2, v0
	v_and_b32_e32 v11, 4, v11
	v_and_b32_e32 v12, 24, v12
	v_or3_b32 v0, v0, v11, v12
	s_ashr_i32 s39, s13, 31
	v_mul_u32_u24_e32 v0, s1, v0
	s_lshr_b32 s1, s39, 29
	s_add_i32 s1, s13, s1
	s_ashr_i32 s4, s35, 6
	s_lshr_b32 s38, s56, 3
	s_ashr_i32 s14, s1, 3
	s_and_b32 s1, s1, -8
	s_ashr_i32 s5, s35, 8
	s_lshl_b32 s36, s31, 18
	s_lshl_b32 s37, s4, 10
	v_and_b32_e32 v9, 0xc0, v9
	s_sub_i32 s1, s13, s1
	s_or_b32 s40, s38, 1
	v_sub_u32_e32 v8, v8, v9
	s_cmp_lt_i32 s1, 0
	v_lshlrev_b32_e32 v11, 5, v7
	v_ashrrev_i16_sdwa v8, v244, sext(v8) dst_sel:DWORD dst_unused:UNUSED_PAD src0_sel:DWORD src1_sel:BYTE_0
	s_cselect_b32 s15, s40, s38
	s_lshl_b32 s41, s0, 3
	v_and_b32_e32 v11, 32, v11
	v_bfe_i32 v8, v8, 0, 16
	s_abs_i32 s42, s41
	v_add_u32_e32 v9, v11, v8
	v_cvt_f32_u32_e32 v11, s42
	v_lshlrev_b32_e32 v10, 11, v10
	v_add_lshl_u32 v0, v0, v9, 1
	v_lshl_add_u32 v134, v9, 1, v10
	v_rcp_iflag_f32_e32 v9, v11
	s_mul_i32 s1, s15, s1
	s_sub_i32 s15, 0, s42
	s_add_i32 s1, s1, s14
	v_mul_f32_e32 v9, 0x4f7ffffe, v9
	v_cvt_u32_f32_e32 v9, v9
	s_ashr_i32 s14, s1, 31
	s_bfe_i32 s43, s0, 0x1001c
	s_xor_b32 s0, s14, s43
	v_readfirstlane_b32 s44, v9
	s_mul_i32 s15, s15, s44
	s_mul_hi_u32 s15, s44, s15
	s_abs_i32 s14, s1
	s_add_i32 s44, s44, s15
	s_mul_hi_u32 s15, s14, s44
	s_mul_i32 s16, s15, s42
	s_sub_i32 s14, s14, s16
	s_add_i32 s16, s15, 1
	s_sub_i32 s17, s14, s42
	s_cmp_ge_u32 s14, s42
	s_cselect_b32 s15, s16, s15
	s_cselect_b32 s14, s17, s14
	s_add_i32 s16, s15, 1
	s_cmp_ge_u32 s14, s42
	s_cselect_b32 s14, s16, s15
	s_xor_b32 s14, s14, s0
	s_sub_i32 s0, s14, s0
	s_lshl_b32 s14, s0, 3
	s_sub_i32 s15, s30, s14
	s_min_i32 s15, s15, 8
	v_cvt_f32_i32_e32 v9, s15
	s_mul_i32 s0, s0, s41
	s_sub_i32 s16, s1, s0
	v_cvt_f32_i32_e32 v10, s16
	v_rcp_iflag_f32_e32 v11, v9
	s_xor_b32 s0, s16, s15
	s_ashr_i32 s0, s0, 30
	s_or_b32 s17, s0, 1
	v_mul_f32_e32 v11, v10, v11
	v_trunc_f32_e32 v11, v11
	v_fma_f32 v10, -v11, v9, v10
	v_cvt_i32_f32_e32 v11, v11
	v_cmp_ge_f32_e64 s[0:1], |v10|, |v9|
	s_and_b64 s[0:1], s[0:1], exec
	s_cselect_b32 s0, s17, 0
	v_readfirstlane_b32 s1, v11
	s_add_i32 s0, s1, s0
	v_cvt_f32_u32_e32 v10, s34
	s_sext_i32_i16 s55, s0
	s_lshl_b32 s18, s55, 8
	s_and_b32 s19, s18, 0xf00
	v_cvt_f32_u32_e32 v11, s19
	v_rcp_iflag_f32_e32 v9, v10
	s_mul_i32 s0, s0, s15
	s_sub_i32 s0, s16, s0
	s_sext_i32_i16 s0, s0
	v_mul_f32_e32 v12, v11, v9
	v_trunc_f32_e32 v12, v12
	v_cvt_u32_f32_e32 v13, v12
	s_add_i32 s14, s14, s0
	s_ashr_i32 s15, s14, 31
	v_fma_f32 v11, -v12, v10, v11
	s_lshl_b64 s[0:1], s[14:15], 19
	v_cmp_ge_f32_e64 s[16:17], |v11|, v10
	v_readfirstlane_b32 s15, v13
	s_cmp_lg_u64 s[16:17], 0
	s_addc_u32 s15, s15, 0
	s_and_b32 s15, s15, 0xffff
	s_mul_i32 s16, s34, s15
	s_sub_i32 s16, s19, s16
	s_and_b32 s17, s18, 0xfffff000
	s_mul_i32 s16, s16, s31
	s_or_b32 s15, s17, s15
	s_add_i32 s16, s15, s16
	s_ashr_i32 s17, s16, 31
	s_lshl_b64 s[16:17], s[16:17], 11
	s_add_u32 s22, s8, s16
	s_addc_u32 s23, s9, s17
	s_add_i32 s15, s37, 0
	s_add_i32 m0, s15, 0x10000
	s_nop 0
	global_load_lds_dwordx4 v0, s[22:23]
	s_add_i32 m0, s15, 0x12000
	s_add_u32 s24, s6, s0
	global_load_lds_dwordx4 v130, s[22:23]
	s_addc_u32 s25, s7, s1
	s_mov_b32 m0, s15
	s_add_i32 s45, s15, 0x2000
	global_load_lds_dwordx4 v134, s[24:25]
	s_mov_b32 m0, s45
	s_add_u32 s0, s22, s36
	global_load_lds_dwordx4 v132, s[24:25]
	s_addc_u32 s1, s23, 0
	s_add_i32 m0, s15, 0x14000
	s_nop 0
	global_load_lds_dwordx4 v0, s[0:1]
	s_add_i32 m0, s15, 0x16000
	s_add_u32 s16, s24, 0x40000
	s_addc_u32 s17, s25, 0
	s_add_i32 s82, s15, 0x4000
	global_load_lds_dwordx4 v130, s[0:1]
	s_mov_b32 m0, s82
	s_add_i32 s83, s15, 0x6000
	global_load_lds_dwordx4 v134, s[16:17]
	s_mov_b32 m0, s83
	s_cmp_lg_u32 s5, 1
	global_load_lds_dwordx4 v132, s[16:17]
	s_cbranch_scc1 .LBB0_93
	s_setprio 3
	s_barrier

; DI int opaque_bid() { int b = blockIdx.x; asm volatile("" : "+s"(b)); return b; }
; #define PG8_STAGE(bufoff, gbase, voff) do { _Pragma("unroll") for (int _i = 0; _i < 2; ++_i) \
;         __builtin_amdgcn_global_load_lds((const unsigned*)((const char*)(gbase) + (voff)[_i]), (LAS unsigned*)(lds + (bufoff) + ldsw + _i * 8192), 16, 0, 0); } while (0)
; #define PG8_BAR __builtin_amdgcn_s_barrier()
; template <class Epi>
; DI void gemm_phase(int wv, LAS unsigned char* lds, const GemmD g, const Epi& E) {
;     ...
;     for (int i = 0; i < 2; ++i) { int R, C; stage_rc(tid * 16 + i * 8192, R, C); const int Rb = Epi::PERM ? ((R & ~31) + perm32(R & 31)) : R;
;         voffA[i] = (unsigned)(R * g.lda + C) * 2u; voffB[i] = (unsigned)(Rb * ldbe + C) * 2u; }
;     const size_t kstep = (size_t)(BK * 2);
;     const size_t hstepA = (size_t)HALF * g.lda * 2, hstepB = (size_t)HALF * ldbe * 2;
;     const unsigned ldsw = (unsigned)wid * 1024u;
;     const int aoff = lds_byte(wr * 64 + fr, fq * 8), boff = lds_byte(wc * 32 + fr, fq * 8);
;     ...
;     StaticOrder S; S.init(g.nM, g.nN, (int)gridDim.x, opaque_bid());
;     Unit cur, nxt; int ui = 0;
;     if (!S.next(0, cur)) return;
;     f32x4 acc[2][2][4][2];
; #pragma unroll
;     for (int a = 0; a < 2; ++a)
; #pragma unroll
;         for (int b = 0; b < 2; ++b)
; #pragma unroll
;             for (int m = 0; m < 4; ++m)
; #pragma unroll
;                 for (int n = 0; n < 2; ++n) acc[a][b][m][n] = (f32x4){0.f, 0.f, 0.f, 0.f};
;     bf16x8 At[4][2], B0[2][2], B1[2][2];
;     ...
;     const char* cA = (const char*)g.A + (size_t)cur.pm * 256 * g.lda * 2; const char* cB = (const char*)g.Bt + PG8_BROW(cur.pn) * (size_t)g.ldb * 2;
;     PG8_STAGE(PG8_SB(0, 0), cB, voffB); PG8_STAGE(PG8_SA(0, 0), cA, voffA); PG8_STAGE(PG8_SB(0, 1), cB + hstepB, voffB); PG8_STAGE(PG8_SA(0, 1), cA + hstepA, voffA);
;     if (wr == 1) PG8_BAR;
.LBB0_480:
	v_ashrrev_i32_e32 v2, 31, v0
	v_lshrrev_b32_e32 v2, 26, v2
	s_waitcnt lgkmcnt(0)
	v_lshlrev_b32_e32 v5, 4, v0
	v_add_u32_e32 v2, v0, v2
	v_bfe_i32 v0, v0, 27, 1
	v_lshrrev_b32_e32 v0, 22, v0
	v_add_u32_e32 v0, v5, v0
	v_and_b32_e32 v0, 0xfffffc00, v0
	v_sub_u32_e32 v0, v5, v0
	v_ashrrev_i32_e32 v2, 6, v2
	v_lshrrev_b32_e32 v3, 4, v0
	v_bitop3_b32 v0, v3, v0, 32 bitop3:0x6c
	v_lshlrev_b32_e32 v3, 3, v2
	v_and_b32_e32 v4, -16, v3
	v_ashrrev_i32_e32 v3, 31, v0
	v_lshrrev_b32_e32 v3, 26, v3
	v_add_u32_e32 v6, v0, v3
	v_ashrrev_i32_e32 v3, 6, v6
	v_add_u32_e32 v7, v3, v4
	v_lshlrev_b32_e32 v4, 5, v2
	v_and_b32_e32 v9, 32, v4
	v_and_b32_e32 v4, 0xc0, v6
	v_sub_u32_e32 v0, v0, v4
	s_add_u32 s76, s48, s0
	v_ashrrev_i16_sdwa v0, v244, sext(v0) dst_sel:DWORD dst_unused:UNUSED_PAD src0_sel:DWORD src1_sel:BYTE_0
	s_addc_u32 s78, s49, s1
	v_bfe_i32 v4, v0, 0, 16
	v_lshlrev_b32_e32 v0, 1, v7
	v_lshrrev_b32_e32 v6, 2, v7
	v_and_b32_e32 v10, 3, v3
	s_mov_b32 s1, 0x1fffe0
	v_and_b32_e32 v0, 24, v0
	v_and_b32_e32 v6, 4, v6
	v_and_or_b32 v10, v7, s1, v10
	v_or3_b32 v0, v10, v6, v0
	v_add_lshl_u32 v6, v9, v4, 1
	v_lshl_add_u32 v130, v7, 11, v6
	v_lshl_add_u32 v0, v0, 11, v6
	v_add_u32_e32 v6, 0x2000, v5
	v_ashrrev_i32_e32 v5, 31, v6
	s_add_i32 s2, s8, s6
	v_lshrrev_b32_e32 v5, 22, v5
	s_ashr_i32 s3, s2, 31
	v_add_u32_e32 v5, v6, v5
	s_lshr_b32 s3, s3, 25
	v_ashrrev_i32_e32 v5, 10, v5
	s_add_i32 s3, s2, s3
	v_mul_i32_i24_e32 v7, 0x400, v5
	s_ashr_i32 s6, s3, 7
	s_and_b32 s3, s3, 0xff80
	v_sub_u32_e32 v6, v6, v7
	s_sub_i32 s2, s2, s3
	v_lshrrev_b32_e32 v7, 4, v6
	s_bfe_i32 s3, s2, 0x80000
	v_bitop3_b32 v7, v7, v6, 32 bitop3:0x6c
	v_lshlrev_b32_e32 v6, 3, v5
	s_bfe_u32 s3, s3, 0x3000c
	v_and_b32_e32 v9, -16, v6
	v_ashrrev_i32_e32 v6, 31, v7
	s_add_i32 s3, s2, s3
	v_lshrrev_b32_e32 v6, 26, v6
	s_bfe_i32 s7, s3, 0x80000
	s_and_b32 s3, s3, 0xf8
	v_add_u32_e32 v10, v7, v6
	s_sext_i32_i16 s7, s7
	s_sub_i32 s2, s2, s3
	v_ashrrev_i32_e32 v6, 6, v10
	s_lshl_b32 s6, s6, 3
	s_sext_i32_i8 s2, s2
	s_ashr_i32 s12, s7, 3
	v_add_u32_e32 v9, v6, v9
	v_and_b32_e32 v13, 3, v6
	s_add_i32 s24, s6, s2
	s_lshl_b32 s8, s12, 8
	v_and_or_b32 v13, v9, s1, v13
	s_ashr_i32 s1, s35, 6
	s_ashr_i32 s25, s24, 31
	s_ashr_i32 s9, s8, 31
	s_ashr_i32 s0, s35, 8
	v_and_b32_e32 v10, 0xc0, v10
	s_lshl_b32 s79, s1, 10
	s_lshl_b64 s[6:7], s[24:25], 19
	s_lshl_b64 s[8:9], s[8:9], 11
	v_sub_u32_e32 v7, v7, v10
	s_add_u32 s28, s39, s8
	v_lshlrev_b32_e32 v11, 5, v5
	v_ashrrev_i16_sdwa v7, v244, sext(v7) dst_sel:DWORD dst_unused:UNUSED_PAD src0_sel:DWORD src1_sel:BYTE_0
	v_lshlrev_b32_e32 v10, 1, v9
	v_lshrrev_b32_e32 v12, 2, v9
	s_addc_u32 s29, s40, s9
	s_add_i32 s25, s79, 0
	v_and_b32_e32 v11, 32, v11
	v_bfe_i32 v7, v7, 0, 16
	v_and_b32_e32 v10, 24, v10
	v_and_b32_e32 v12, 4, v12
	s_add_i32 m0, s25, 0x10000
	v_or3_b32 v10, v13, v12, v10
	v_add_lshl_u32 v11, v11, v7, 1
	global_load_lds_dwordx4 v0, s[28:29]
	s_add_i32 m0, s25, 0x12000
	v_lshl_add_u32 v134, v10, 11, v11
	s_add_u32 s26, s76, s6
	global_load_lds_dwordx4 v134, s[28:29]
	s_addc_u32 s27, s78, s7
	s_mov_b32 m0, s25
	s_add_i32 s80, s25, 0x2000
	v_lshl_add_u32 v132, v9, 11, v11
	global_load_lds_dwordx4 v130, s[26:27]
	s_mov_b32 m0, s80
	s_add_u32 s6, s28, 0x40000
	global_load_lds_dwordx4 v132, s[26:27]
	s_addc_u32 s7, s29, 0
	s_add_i32 m0, s25, 0x14000
	s_nop 0
	global_load_lds_dwordx4 v0, s[6:7]
	s_add_i32 m0, s25, 0x16000
	s_nop 0
	global_load_lds_dwordx4 v134, s[6:7]
	s_add_u32 s6, s26, 0x40000
	s_addc_u32 s7, s27, 0
	s_add_i32 s81, s25, 0x4000
	s_mov_b32 m0, s81
	s_add_i32 s82, s25, 0x6000
	global_load_lds_dwordx4 v130, s[6:7]
	s_mov_b32 m0, s82
	s_cmp_lg_u32 s0, 1
	global_load_lds_dwordx4 v132, s[6:7]
	s_cbranch_scc1 .LBB0_482
	s_setprio 3
	s_barrier

; DI int opaque_bid() { int b = blockIdx.x; asm volatile("" : "+s"(b)); return b; }
; #define PG8_STAGE(bufoff, gbase, voff) do { _Pragma("unroll") for (int _i = 0; _i < 2; ++_i) \
;         __builtin_amdgcn_global_load_lds((const unsigned*)((const char*)(gbase) + (voff)[_i]), (LAS unsigned*)(lds + (bufoff) + ldsw + _i * 8192), 16, 0, 0); } while (0)
; #define PG8_BAR __builtin_amdgcn_s_barrier()
; template <class Epi>
; DI void gemm_phase(int wv, LAS unsigned char* lds, const GemmD g, const Epi& E) {
;     ...
;     for (int i = 0; i < 2; ++i) { int R, C; stage_rc(tid * 16 + i * 8192, R, C); const int Rb = Epi::PERM ? ((R & ~31) + perm32(R & 31)) : R;
;         voffA[i] = (unsigned)(R * g.lda + C) * 2u; voffB[i] = (unsigned)(Rb * ldbe + C) * 2u; }
;     const size_t kstep = (size_t)(BK * 2);
;     const size_t hstepA = (size_t)HALF * g.lda * 2, hstepB = (size_t)HALF * ldbe * 2;
;     const unsigned ldsw = (unsigned)wid * 1024u;
;     const int aoff = lds_byte(wr * 64 + fr, fq * 8), boff = lds_byte(wc * 32 + fr, fq * 8);
;     ...
;     StaticOrder S; S.init(g.nM, g.nN, (int)gridDim.x, opaque_bid());
;     Unit cur, nxt; int ui = 0;
;     if (!S.next(0, cur)) return;
;     f32x4 acc[2][2][4][2];
; #pragma unroll
;     for (int a = 0; a < 2; ++a)
; #pragma unroll
;         for (int b = 0; b < 2; ++b)
; #pragma unroll
;             for (int m = 0; m < 4; ++m)
; #pragma unroll
;                 for (int n = 0; n < 2; ++n) acc[a][b][m][n] = (f32x4){0.f, 0.f, 0.f, 0.f};
;     bf16x8 At[4][2], B0[2][2], B1[2][2];
;     ...
;     const char* cA = (const char*)g.A + (size_t)cur.pm * 256 * g.lda * 2; const char* cB = (const char*)g.Bt + PG8_BROW(cur.pn) * (size_t)g.ldb * 2;
;     PG8_STAGE(PG8_SB(0, 0), cB, voffB); PG8_STAGE(PG8_SA(0, 0), cA, voffA); PG8_STAGE(PG8_SB(0, 1), cB + hstepB, voffB); PG8_STAGE(PG8_SA(0, 1), cA + hstepA, voffA);
;     if (wr == 1) PG8_BAR;
.LBB0_534:
	v_ashrrev_i32_e32 v3, 31, v0
	v_lshrrev_b32_e32 v3, 26, v3
	v_lshlrev_b32_e32 v2, 4, v0
	v_add_u32_e32 v3, v0, v3
	v_bfe_i32 v0, v0, 27, 1
	v_lshrrev_b32_e32 v0, 22, v0
	v_add_u32_e32 v0, v2, v0
	v_and_b32_e32 v0, 0xfffffc00, v0
	v_sub_u32_e32 v0, v2, v0
	v_lshrrev_b32_e32 v4, 4, v0
	v_bitop3_b32 v0, v4, v0, 32 bitop3:0x6c
	s_waitcnt lgkmcnt(0)
	v_ashrrev_i32_e32 v5, 31, v0
	v_lshrrev_b32_e32 v5, 26, v5
	v_ashrrev_i32_e32 v3, 6, v3
	v_add_u32_e32 v5, v0, v5
	s_and_b64 s[12:13], s[4:5], exec
	v_readlane_b32 s2, v253, 36
	v_lshlrev_b32_e32 v4, 3, v3
	v_ashrrev_i32_e32 v6, 6, v5
	v_and_b32_e32 v5, 0xc0, v5
	v_readlane_b32 s3, v253, 37
	s_cselect_b32 s81, s2, s10
	s_cselect_b32 s2, 0, 0xa00000
	v_and_b32_e32 v4, -16, v4
	v_lshlrev_b32_e32 v3, 5, v3
	v_sub_u32_e32 v0, v0, v5
	s_cselect_b32 s80, s3, s11
	s_cselect_b32 s16, 0x400, s77
	s_add_u32 s82, s15, s2
	v_readlane_b32 s2, v253, 30
	v_add_u32_e32 v4, v6, v4
	v_and_b32_e32 v3, 32, v3
	v_ashrrev_i16_sdwa v0, v244, sext(v0) dst_sel:DWORD dst_unused:UNUSED_PAD src0_sel:DWORD src1_sel:BYTE_0
	s_addc_u32 s83, s2, 0
	s_ashr_i32 s13, s78, 6
	v_add_u32_sdwa v0, v3, sext(v0) dst_sel:DWORD dst_unused:UNUSED_PAD src0_sel:DWORD src1_sel:WORD_0
	v_lshlrev_b32_e32 v3, 1, v4
	v_lshrrev_b32_e32 v5, 2, v4
	v_and_b32_e32 v6, 3, v6
	s_mov_b32 s3, 0x7fffffe0
	v_and_b32_e32 v3, 24, v3
	v_and_b32_e32 v5, 4, v5
	v_and_or_b32 v6, v4, s3, v6
	s_and_b64 s[18:19], s[4:5], exec
	v_or3_b32 v3, v6, v5, v3
	s_cselect_b32 s2, 10, 12
	v_lshlrev_b32_e32 v4, s2, v4
	v_lshlrev_b32_e32 v3, s2, v3
	v_add_u32_e32 v2, 0x2000, v2
	v_add_lshl_u32 v130, v0, v4, 1
	v_add_lshl_u32 v0, v3, v0, 1
	v_ashrrev_i32_e32 v3, 31, v2
	v_lshrrev_b32_e32 v3, 22, v3
	v_add_u32_e32 v3, v2, v3
	v_ashrrev_i32_e32 v3, 10, v3
	v_mul_i32_i24_e32 v4, 0x400, v3
	v_sub_u32_e32 v2, v2, v4
	v_lshrrev_b32_e32 v4, 4, v2
	v_bitop3_b32 v2, v4, v2, 32 bitop3:0x6c
	v_ashrrev_i32_e32 v5, 31, v2
	v_lshrrev_b32_e32 v5, 26, v5
	v_add_u32_e32 v5, v2, v5
	v_lshlrev_b32_e32 v4, 3, v3
	v_ashrrev_i32_e32 v6, 6, v5
	v_and_b32_e32 v5, 0xc0, v5
	v_and_b32_e32 v4, -16, v4
	v_lshlrev_b32_e32 v3, 5, v3
	v_sub_u32_e32 v2, v2, v5
	v_add_u32_e32 v4, v6, v4
	v_and_b32_e32 v3, 32, v3
	v_ashrrev_i16_sdwa v2, v244, sext(v2) dst_sel:DWORD dst_unused:UNUSED_PAD src0_sel:DWORD src1_sel:BYTE_0
	v_add_u32_sdwa v2, v3, sext(v2) dst_sel:DWORD dst_unused:UNUSED_PAD src0_sel:DWORD src1_sel:WORD_0
	v_lshlrev_b32_e32 v3, 1, v4
	v_lshrrev_b32_e32 v5, 2, v4
	v_and_b32_e32 v6, 3, v6
	v_and_b32_e32 v3, 24, v3
	v_and_b32_e32 v5, 4, v5
	v_and_or_b32 v6, v4, s3, v6
	v_or3_b32 v3, v6, v5, v3
	v_lshlrev_b32_e32 v4, s2, v4
	v_lshlrev_b32_e32 v3, s2, v3
	s_add_i32 s2, s8, s6
	s_ashr_i32 s3, s2, 31
	s_lshr_b32 s3, s3, 27
	s_add_i32 s3, s2, s3
	s_ashr_i32 s6, s3, 5
	s_and_b32 s3, s3, 0xffe0
	s_sub_i32 s2, s2, s3
	s_bfe_i32 s3, s2, 0x80000
	s_bfe_u32 s3, s3, 0x3000c
	s_add_i32 s3, s2, s3
	s_bfe_i32 s7, s3, 0x80000
	s_and_b32 s3, s3, 0xf8
	s_sub_i32 s2, s2, s3
	s_lshl_b32 s6, s6, 3
	s_sext_i32_i8 s2, s2
	s_sext_i32_i16 s7, s7
	s_add_i32 s8, s6, s2
	s_ashr_i32 s17, s78, 8
	s_lshl_b32 s56, s16, 8
	s_lshl_b32 s84, s13, 10
	s_ashr_i32 s12, s7, 3
	s_ashr_i32 s9, s8, 31
	s_and_b64 s[6:7], s[4:5], exec
	s_cselect_b32 s85, 19, 21
	s_lshl_b32 s18, s12, 8
	s_lshl_b64 s[6:7], s[8:9], s85
	s_ashr_i32 s19, s18, 31
	s_and_b64 s[22:23], s[4:5], exec
	s_cselect_b32 s9, 11, 13
	s_lshl_b64 s[18:19], s[18:19], s9
	s_add_u32 s30, s82, s18
	s_addc_u32 s31, s83, s19
	s_add_i32 s86, s84, 0
	s_add_i32 m0, s86, 0x10000
	v_add_lshl_u32 v134, v3, v2, 1
	global_load_lds_dwordx4 v0, s[30:31]
	s_add_i32 m0, s86, 0x12000
	s_add_u32 s28, s81, s6
	global_load_lds_dwordx4 v134, s[30:31]
	s_addc_u32 s29, s80, s7
	s_mov_b32 m0, s86
	s_add_i32 s87, s86, 0x2000
	v_add_lshl_u32 v132, v2, v4, 1
	global_load_lds_dwordx4 v130, s[28:29]
	s_mov_b32 m0, s87
	s_add_u32 s6, s30, s56
	global_load_lds_dwordx4 v132, s[28:29]
	s_addc_u32 s7, s31, 0
	s_add_i32 m0, s86, 0x14000
	v_mov_b32_e32 v135, v1
	global_load_lds_dwordx4 v0, s[6:7]
	s_add_i32 m0, s86, 0x16000
	v_lshl_add_u64 v[10:11], s[6:7], 0, v[0:1]
	v_lshl_add_u64 v[12:13], s[6:7], 0, v[134:135]
	global_load_lds_dwordx4 v134, s[6:7]
	s_add_u32 s6, s28, s56
	s_addc_u32 s7, s29, 0
	s_add_i32 s74, s86, 0x4000
	s_mov_b32 m0, s74
	s_add_i32 s41, s86, 0x6000
	global_load_lds_dwordx4 v130, s[6:7]
	s_mov_b32 m0, s41
	v_mov_b32_e32 v131, v1
	global_load_lds_dwordx4 v132, s[6:7]
	v_mov_b32_e32 v133, v1
	v_lshl_add_u64 v[2:3], s[30:31], 0, v[0:1]
	v_lshl_add_u64 v[4:5], s[30:31], 0, v[134:135]
	v_lshl_add_u64 v[6:7], s[28:29], 0, v[130:131]
	v_lshl_add_u64 v[8:9], s[28:29], 0, v[132:133]
	s_cmp_lg_u32 s17, 1
	s_cbranch_scc1 .LBB0_536
	s_setprio 3
	s_barrier
